# P2 even mixer: mask-free copy of score blocks for interior key tiles (window/seq mask all-true): no cndmask/cmp/index adds
# baseline (speedup 1.0000x reference)
.LBB0_259:
	s_cmp_eq_u32 s9, 0xffffff80
	s_cbranch_scc1 .Lm_259
	s_cmp_eq_u32 s9, 0xffffffc0
	s_cbranch_scc0 .Lm_t3
	s_cmp_le_i32 s8, 0xffffffc0
	s_cbranch_scc1 .Lm_259
	s_branch .Lm_orig
.Lm_t3:
	s_cmp_eq_u32 s9, 0xffffff40
	s_cbranch_scc0 .Lm_orig
	s_cmp_ge_i32 s8, 0xfffff080
	s_cbranch_scc1 .Lm_259

.Lm_259:
	s_and_b32 s10, s33, 1
	s_mul_i32 s11, s10, 0x9100
	s_add_i32 s14, s11, 0
	v_add3_u32 v216, s14, v208, v178
	v_add_u32_e32 v96, v216, v209
	ds_read_b128 v[64:67], v96
	ds_read_b128 v[68:71], v96 offset:32
	ds_read_b128 v[72:75], v96 offset:64
	ds_read_b128 v[76:79], v96 offset:96
	s_add_i32 s40, s8, s9
	s_waitcnt lgkmcnt(3)
	v_mfma_f32_32x32x16_bf16 v[112:127], v[64:67], v[128:131], 0
	s_add_i32 s11, s40, 0x80
	s_addk_i32 s40, 0x107f
	v_lshl_add_u32 v224, v186, 2, s14
	s_waitcnt lgkmcnt(2)
	v_mfma_f32_32x32x16_bf16 v[112:127], v[68:71], v[132:135], v[112:127]
	v_mfma_f32_32x32x16_bf16 v[80:95], v[64:67], v[152:155], 0
	ds_read_b128 v[64:67], v96 offset:4608
	ds_read_b128 v[218:221], v96 offset:4640
	ds_read_b128 v[226:229], v96 offset:4672
	ds_read_b128 v[230:233], v96 offset:4704
	ds_read_b128 v[234:237], v224 offset:36880
	s_waitcnt lgkmcnt(0)
	v_sub_f32_e32 v222, v201, v234
	v_mfma_f32_32x32x16_bf16 v[112:127], v[72:75], v[136:139], v[112:127]
	v_mfma_f32_32x32x16_bf16 v[80:95], v[68:71], v[144:147], v[80:95]
	v_mfma_f32_32x32x16_bf16 v[112:127], v[76:79], v[140:143], v[112:127]
	v_mfma_f32_32x32x16_bf16 v[80:95], v[72:75], v[148:151], v[80:95]
	ds_read_b128 v[68:71], v224 offset:36864
	s_waitcnt lgkmcnt(0)
	v_sub_f32_e32 v68, v201, v68
	s_nop 5
	s_nop 1
	v_fma_f32 v217, -v207, |v68|, v112
	v_sub_f32_e32 v68, v201, v69
	v_fma_f32 v113, -v207, |v68|, v113
	v_sub_f32_e32 v69, v201, v70
	v_fma_f32 v114, -v207, |v69|, v114
	v_max3_f32 v68, v217, s31, v113
	v_sub_f32_e32 v69, v201, v71
	v_fma_f32 v115, -v207, |v69|, v115
	v_mfma_f32_32x32x16_bf16 v[80:95], v[76:79], v[156:159], v[80:95]
	v_fma_f32 v116, -v207, |v222|, v116
	v_max3_f32 v112, v68, v114, v115
	v_sub_f32_e32 v222, v201, v235
	v_fma_f32 v117, -v207, |v222|, v117
	v_mfma_f32_32x32x16_bf16 v[96:111], v[64:67], v[128:131], 0
	v_mfma_f32_32x32x16_bf16 v[64:79], v[64:67], v[152:155], 0
	v_mfma_f32_32x32x16_bf16 v[96:111], v[218:221], v[132:135], v[96:111]
	v_mfma_f32_32x32x16_bf16 v[64:79], v[218:221], v[144:147], v[64:79]
	v_sub_f32_e32 v218, v201, v236
	v_fma_f32 v118, -v207, |v218|, v118
	v_mfma_f32_32x32x16_bf16 v[96:111], v[226:229], v[136:139], v[96:111]
	v_sub_f32_e32 v218, v201, v237
	v_fma_f32 v119, -v207, |v218|, v119
	v_max3_f32 v112, v112, v116, v117
	v_mfma_f32_32x32x16_bf16 v[64:79], v[226:229], v[148:151], v[64:79]
	v_max3_f32 v112, v112, v118, v119
	v_mfma_f32_32x32x16_bf16 v[96:111], v[230:233], v[140:143], v[96:111]
	v_mfma_f32_32x32x16_bf16 v[64:79], v[230:233], v[156:159], v[64:79]
	ds_read_b128 v[218:221], v224 offset:36928
	ds_read_b128 v[226:229], v224 offset:36944
	s_waitcnt lgkmcnt(1)
	v_sub_f32_e32 v218, v201, v218
	v_fma_f32 v120, -v207, |v218|, v120
	v_sub_f32_e32 v219, v201, v219
	v_sub_f32_e32 v218, v201, v220
	v_fma_f32 v121, -v207, |v219|, v121
	v_fma_f32 v122, -v207, |v218|, v122
	v_sub_f32_e32 v218, v201, v221
	v_fma_f32 v123, -v207, |v218|, v123
	s_waitcnt lgkmcnt(0)
	v_sub_f32_e32 v218, v201, v226
	v_fma_f32 v124, -v207, |v218|, v124
	v_sub_f32_e32 v218, v201, v227
	v_fma_f32 v125, -v207, |v218|, v125
	v_sub_f32_e32 v218, v201, v228
	v_fma_f32 v126, -v207, |v218|, v126
	v_sub_f32_e32 v218, v201, v229
	v_max3_f32 v112, v112, v120, v121
	v_fma_f32 v127, -v207, |v218|, v127
	v_max3_f32 v112, v112, v122, v123
	v_max3_f32 v112, v112, v124, v125
	v_max3_f32 v112, v112, v126, v127
	ds_read_b128 v[218:221], v224 offset:36992
	ds_read_b128 v[226:229], v224 offset:37008
	s_waitcnt lgkmcnt(1)
	v_sub_f32_e32 v218, v201, v218
	v_sub_f32_e32 v219, v201, v219
	v_fma_f32 v218, -v207, |v218|, v96
	v_fma_f32 v219, -v207, |v219|, v97
	v_sub_f32_e32 v97, v201, v220
	v_fma_f32 v220, -v207, |v97|, v98
	v_max3_f32 v96, v112, v218, v219
	v_sub_f32_e32 v97, v201, v221
	v_fma_f32 v221, -v207, |v97|, v99
	s_waitcnt lgkmcnt(0)
	v_sub_f32_e32 v97, v201, v226
	v_fma_f32 v222, -v207, |v97|, v100
	v_max3_f32 v96, v96, v220, v221
	v_sub_f32_e32 v97, v201, v227
	v_fma_f32 v223, -v207, |v97|, v101
	v_sub_f32_e32 v97, v201, v228
	v_fma_f32 v112, -v207, |v97|, v102
	v_max3_f32 v96, v96, v222, v223
	v_sub_f32_e32 v97, v201, v229
	v_fma_f32 v103, -v207, |v97|, v103
	v_max3_f32 v100, v96, v112, v103
	ds_read_b128 v[96:99], v224 offset:37056
	ds_read_b128 v[226:229], v224 offset:37072
	s_waitcnt lgkmcnt(1)
	v_sub_f32_e32 v96, v201, v96
	v_sub_f32_e32 v97, v201, v97
	v_fma_f32 v104, -v207, |v96|, v104
	v_fma_f32 v101, -v207, |v97|, v105
	v_sub_f32_e32 v96, v201, v98
	v_fma_f32 v102, -v207, |v96|, v106
	v_max3_f32 v97, v100, v104, v101
	v_sub_f32_e32 v96, v201, v99
	v_fma_f32 v96, -v207, |v96|, v107
	v_max3_f32 v98, v97, v102, v96
	s_waitcnt lgkmcnt(0)
	v_sub_f32_e32 v97, v201, v226
	v_fma_f32 v97, -v207, |v97|, v108
	v_sub_f32_e32 v99, v201, v227
	v_fma_f32 v99, -v207, |v99|, v109
	v_max3_f32 v105, v98, v97, v99
	v_sub_f32_e32 v98, v201, v228
	v_fma_f32 v98, -v207, |v98|, v110
	v_sub_f32_e32 v100, v201, v229
	v_fma_f32 v100, -v207, |v100|, v111
	v_max3_f32 v105, v105, v98, v100
	v_sub_f32_e32 v106, v105, v214
	v_cmp_lt_f32_e32 vcc, s34, v106
	s_cbranch_vccnz .Lm_263
.Lm_260:
	ds_read_b128 v[106:109], v224 offset:36864
	ds_read_b128 v[230:233], v224 offset:36880
	s_waitcnt lgkmcnt(1)
	v_sub_f32_e32 v106, v203, v106
	v_fma_f32 v225, -v207, |v106|, v80
	v_sub_f32_e32 v80, v203, v107
	v_fma_f32 v226, -v207, |v80|, v81
	v_sub_f32_e32 v81, v203, v108
	v_fma_f32 v227, -v207, |v81|, v82
	v_max3_f32 v80, v225, s31, v226
	v_sub_f32_e32 v81, v203, v109
	v_fma_f32 v228, -v207, |v81|, v83
	s_waitcnt lgkmcnt(0)
	v_sub_f32_e32 v81, v203, v230
	v_fma_f32 v229, -v207, |v81|, v84
	v_max3_f32 v80, v80, v227, v228
	v_sub_f32_e32 v81, v203, v231
	v_fma_f32 v230, -v207, |v81|, v85
	v_sub_f32_e32 v81, v203, v232
	v_fma_f32 v231, -v207, |v81|, v86
	v_max3_f32 v80, v80, v229, v230
	v_sub_f32_e32 v81, v203, v233
	v_fma_f32 v232, -v207, |v81|, v87
	v_max3_f32 v81, v80, v231, v232
	ds_read_b128 v[82:85], v224 offset:36928
	ds_read_b128 v[106:109], v224 offset:36944
	s_waitcnt lgkmcnt(1)
	v_sub_f32_e32 v82, v203, v82
	v_sub_f32_e32 v83, v203, v83
	v_fma_f32 v82, -v207, |v82|, v88
	v_fma_f32 v80, -v207, |v83|, v89
	v_sub_f32_e32 v83, v203, v84
	v_fma_f32 v83, -v207, |v83|, v90
	v_sub_f32_e32 v84, v203, v85
	v_fma_f32 v86, -v207, |v84|, v91
	v_max3_f32 v81, v81, v82, v80
	s_waitcnt lgkmcnt(0)
	v_sub_f32_e32 v84, v203, v106
	v_fma_f32 v88, -v207, |v84|, v92
	v_max3_f32 v81, v81, v83, v86
	v_sub_f32_e32 v84, v203, v107
	v_fma_f32 v90, -v207, |v84|, v93
	v_sub_f32_e32 v84, v203, v108
	v_fma_f32 v92, -v207, |v84|, v94
	v_max3_f32 v81, v81, v88, v90
	v_sub_f32_e32 v84, v203, v109
	v_fma_f32 v94, -v207, |v84|, v95
	v_max3_f32 v85, v81, v92, v94
	ds_read_b128 v[106:109], v224 offset:36992
	ds_read_b128 v[234:237], v224 offset:37008
	s_waitcnt lgkmcnt(1)
	v_sub_f32_e32 v84, v203, v106
	v_sub_f32_e32 v87, v203, v107
	v_fma_f32 v84, -v207, |v84|, v64
	v_fma_f32 v81, -v207, |v87|, v65
	v_sub_f32_e32 v65, v203, v108
	v_fma_f32 v65, -v207, |v65|, v66
	v_max3_f32 v64, v85, v84, v81
	v_mov_b32_e32 v85, v65
	v_sub_f32_e32 v65, v203, v109
	v_fma_f32 v87, -v207, |v65|, v67
	s_waitcnt lgkmcnt(0)
	v_sub_f32_e32 v65, v203, v234
	v_fma_f32 v89, -v207, |v65|, v68
	v_max3_f32 v64, v64, v85, v87
	v_sub_f32_e32 v65, v203, v235
	v_fma_f32 v91, -v207, |v65|, v69
	v_sub_f32_e32 v65, v203, v236
	v_fma_f32 v93, -v207, |v65|, v70
	v_max3_f32 v64, v64, v89, v91
	v_sub_f32_e32 v65, v203, v237
	v_fma_f32 v95, -v207, |v65|, v71
	v_max3_f32 v106, v64, v93, v95
	ds_read_b128 v[64:67], v224 offset:37056
	ds_read_b128 v[68:71], v224 offset:37072
	s_waitcnt lgkmcnt(1)
	v_sub_f32_e32 v64, v203, v64
	v_sub_f32_e32 v65, v203, v65
	v_fma_f32 v64, -v207, |v64|, v72
	v_fma_f32 v65, -v207, |v65|, v73
	v_sub_f32_e32 v66, v203, v66
	v_fma_f32 v66, -v207, |v66|, v74
	v_sub_f32_e32 v67, v203, v67
	v_fma_f32 v67, -v207, |v67|, v75
	s_waitcnt lgkmcnt(0)
	v_sub_f32_e32 v68, v203, v68
	v_fma_f32 v68, -v207, |v68|, v76
	v_sub_f32_e32 v69, v203, v69
	v_fma_f32 v69, -v207, |v69|, v77
	v_sub_f32_e32 v70, v203, v70
	v_max3_f32 v72, v106, v64, v65
	v_fma_f32 v70, -v207, |v70|, v78
	v_sub_f32_e32 v71, v203, v71
	v_max3_f32 v72, v72, v66, v67
	v_fma_f32 v71, -v207, |v71|, v79
	v_max3_f32 v72, v72, v68, v69
	v_max3_f32 v72, v72, v70, v71
	v_sub_f32_e32 v73, v72, v215
	v_cmp_lt_f32_e32 vcc, s34, v73
	s_cbranch_vccnz .LBB0_264
	s_branch .LBB0_261
.Lm_263:
	v_mov_b32_e32 v106, v105
	s_nop 1
	v_permlane32_swap_b32_e32 v105, v106
	v_max3_f32 v105, v214, v105, v106
	v_sub_f32_e32 v106, v214, v105
	v_exp_f32_e32 v106, v106
	v_mov_b32_e32 v214, v105
	v_mul_f32_e32 v202, v202, v106
	v_pk_mul_f32 v[62:63], v[62:63], v[106:107] op_sel_hi:[1,0]
	v_pk_mul_f32 v[60:61], v[60:61], v[106:107] op_sel_hi:[1,0]
	v_pk_mul_f32 v[58:59], v[58:59], v[106:107] op_sel_hi:[1,0]
	v_pk_mul_f32 v[56:57], v[56:57], v[106:107] op_sel_hi:[1,0]
	v_pk_mul_f32 v[54:55], v[54:55], v[106:107] op_sel_hi:[1,0]
	v_pk_mul_f32 v[52:53], v[52:53], v[106:107] op_sel_hi:[1,0]
	v_pk_mul_f32 v[50:51], v[50:51], v[106:107] op_sel_hi:[1,0]
	v_pk_mul_f32 v[48:49], v[48:49], v[106:107] op_sel_hi:[1,0]
	v_pk_mul_f32 v[46:47], v[46:47], v[106:107] op_sel_hi:[1,0]
	v_pk_mul_f32 v[44:45], v[44:45], v[106:107] op_sel_hi:[1,0]
	v_pk_mul_f32 v[42:43], v[42:43], v[106:107] op_sel_hi:[1,0]
	v_pk_mul_f32 v[40:41], v[40:41], v[106:107] op_sel_hi:[1,0]
	v_pk_mul_f32 v[38:39], v[38:39], v[106:107] op_sel_hi:[1,0]
	v_pk_mul_f32 v[36:37], v[36:37], v[106:107] op_sel_hi:[1,0]
	v_pk_mul_f32 v[34:35], v[34:35], v[106:107] op_sel_hi:[1,0]
	v_pk_mul_f32 v[32:33], v[32:33], v[106:107] op_sel_hi:[1,0]
	s_branch .Lm_260
.LBB0_265:
	v_mov_b32_e32 v64, v202
	s_nop 1
	v_permlane32_swap_b32_e32 v202, v64
	v_add_f32_e32 v64, v202, v64
	v_div_scale_f32 v65, s[8:9], v64, v64, 1.0
	v_rcp_f32_e32 v66, v65
	v_lshlrev_b32_e32 v67, 2, v184
	v_lshlrev_b32_e32 v68, 2, v200
	v_add3_u32 v72, 0, v67, v68
	v_fma_f32 v67, -v65, v66, 1.0
	v_fmac_f32_e32 v66, v67, v66
	v_div_scale_f32 v67, vcc, 1.0, v64, 1.0
	v_mul_f32_e32 v68, v67, v66
	v_fma_f32 v69, -v65, v68, v67
	v_fmac_f32_e32 v68, v69, v66
	v_fma_f32 v65, -v65, v68, v67
	v_div_fmas_f32 v65, v65, v66, v68
	v_div_fixup_f32 v74, v65, v64, 1.0
	v_pk_mul_f32 v[70:71], v[48:49], v[74:75] op_sel_hi:[1,0]
	v_pk_mul_f32 v[68:69], v[50:51], v[74:75] op_sel_hi:[1,0]
	v_mul_f32_e32 v50, v71, v71
	v_fmac_f32_e32 v50, v70, v70
	v_fmac_f32_e32 v50, v68, v68
	v_pk_mul_f32 v[66:67], v[52:53], v[74:75] op_sel_hi:[1,0]
	v_fmac_f32_e32 v50, v69, v69
	v_fmac_f32_e32 v50, v66, v66
	v_pk_mul_f32 v[64:65], v[54:55], v[74:75] op_sel_hi:[1,0]
	v_fmac_f32_e32 v50, v67, v67
	v_fmac_f32_e32 v50, v64, v64
	v_pk_mul_f32 v[56:57], v[56:57], v[74:75] op_sel_hi:[1,0]
	v_fmac_f32_e32 v50, v65, v65
	v_fmac_f32_e32 v50, v56, v56
	v_pk_mul_f32 v[58:59], v[58:59], v[74:75] op_sel_hi:[1,0]
	v_fmac_f32_e32 v50, v57, v57
	v_fmac_f32_e32 v50, v58, v58
	v_pk_mul_f32 v[60:61], v[60:61], v[74:75] op_sel_hi:[1,0]
	v_fmac_f32_e32 v50, v59, v59
	v_fmac_f32_e32 v50, v60, v60
	v_pk_mul_f32 v[62:63], v[62:63], v[74:75] op_sel_hi:[1,0]
	v_fmac_f32_e32 v50, v61, v61
	v_fmac_f32_e32 v50, v62, v62
	v_fmac_f32_e32 v50, v63, v63
	v_pk_mul_f32 v[54:55], v[32:33], v[74:75] op_sel_hi:[1,0]
	v_pk_mul_f32 v[52:53], v[34:35], v[74:75] op_sel_hi:[1,0]
	v_fmac_f32_e32 v50, v54, v54
	v_fmac_f32_e32 v50, v55, v55
	v_fmac_f32_e32 v50, v52, v52
	v_pk_mul_f32 v[48:49], v[36:37], v[74:75] op_sel_hi:[1,0]
	v_fmac_f32_e32 v50, v53, v53
	v_fmac_f32_e32 v50, v48, v48
	v_pk_mul_f32 v[38:39], v[38:39], v[74:75] op_sel_hi:[1,0]
	v_fmac_f32_e32 v50, v49, v49
	v_fmac_f32_e32 v50, v38, v38
	v_pk_mul_f32 v[40:41], v[40:41], v[74:75] op_sel_hi:[1,0]
	v_fmac_f32_e32 v50, v39, v39
	v_fmac_f32_e32 v50, v40, v40
	v_pk_mul_f32 v[42:43], v[42:43], v[74:75] op_sel_hi:[1,0]
	v_fmac_f32_e32 v50, v41, v41
	v_fmac_f32_e32 v50, v42, v42
	v_pk_mul_f32 v[44:45], v[44:45], v[74:75] op_sel_hi:[1,0]
	v_fmac_f32_e32 v50, v43, v43
	v_fmac_f32_e32 v50, v44, v44
	v_pk_mul_f32 v[46:47], v[46:47], v[74:75] op_sel_hi:[1,0]
	v_fmac_f32_e32 v50, v45, v45
	v_fmac_f32_e32 v50, v46, v46
	v_fmac_f32_e32 v50, v47, v47
	v_mov_b32_e32 v32, v50
	s_nop 1
	v_permlane32_swap_b32_e32 v50, v32
	s_and_saveexec_b64 s[42:43], s[0:1]
	v_add_f32_e32 v32, v50, v32
	ds_write_b32 v72, v32
	s_or_b64 exec, exec, s[42:43]
	v_mov_b32_e32 v32, v181
	s_nop 1
	v_permlane32_swap_b32_e32 v181, v32
	v_add_f32_e32 v32, v181, v32
	v_div_scale_f32 v33, s[8:9], v32, v32, 1.0
	v_rcp_f32_e32 v34, v33
	s_nop 0
	v_fma_f32 v35, -v33, v34, 1.0
	v_fmac_f32_e32 v34, v35, v34
	v_div_scale_f32 v35, vcc, 1.0, v32, 1.0
	v_mul_f32_e32 v36, v35, v34
	v_fma_f32 v37, -v33, v36, v35
	v_fmac_f32_e32 v36, v37, v34
	v_fma_f32 v33, -v33, v36, v35
	v_div_fmas_f32 v33, v33, v34, v36
	v_div_fixup_f32 v34, v33, v32, 1.0
	v_pk_mul_f32 v[16:17], v[16:17], v[34:35] op_sel_hi:[1,0]
	v_pk_mul_f32 v[18:19], v[18:19], v[34:35] op_sel_hi:[1,0]
	v_mul_f32_e32 v32, v17, v17
	v_fmac_f32_e32 v32, v16, v16
	v_fmac_f32_e32 v32, v18, v18
	v_pk_mul_f32 v[20:21], v[20:21], v[34:35] op_sel_hi:[1,0]
	v_fmac_f32_e32 v32, v19, v19
	v_fmac_f32_e32 v32, v20, v20
	v_pk_mul_f32 v[22:23], v[22:23], v[34:35] op_sel_hi:[1,0]
	v_fmac_f32_e32 v32, v21, v21
	v_fmac_f32_e32 v32, v22, v22
	v_pk_mul_f32 v[24:25], v[24:25], v[34:35] op_sel_hi:[1,0]
	v_fmac_f32_e32 v32, v23, v23
	v_fmac_f32_e32 v32, v24, v24
	v_pk_mul_f32 v[26:27], v[26:27], v[34:35] op_sel_hi:[1,0]
	v_fmac_f32_e32 v32, v25, v25
	v_fmac_f32_e32 v32, v26, v26
	v_pk_mul_f32 v[28:29], v[28:29], v[34:35] op_sel_hi:[1,0]
	v_fmac_f32_e32 v32, v27, v27
	v_fmac_f32_e32 v32, v28, v28
	v_pk_mul_f32 v[30:31], v[30:31], v[34:35] op_sel_hi:[1,0]
	v_fmac_f32_e32 v32, v29, v29
	v_fmac_f32_e32 v32, v30, v30
	v_fmac_f32_e32 v32, v31, v31
	v_pk_mul_f32 v[0:1], v[0:1], v[34:35] op_sel_hi:[1,0]
	v_pk_mul_f32 v[2:3], v[2:3], v[34:35] op_sel_hi:[1,0]
	v_fmac_f32_e32 v32, v0, v0
	v_fmac_f32_e32 v32, v1, v1
	v_fmac_f32_e32 v32, v2, v2
	v_pk_mul_f32 v[4:5], v[4:5], v[34:35] op_sel_hi:[1,0]
	v_fmac_f32_e32 v32, v3, v3
	v_fmac_f32_e32 v32, v4, v4
	v_pk_mul_f32 v[6:7], v[6:7], v[34:35] op_sel_hi:[1,0]
	v_fmac_f32_e32 v32, v5, v5
	v_fmac_f32_e32 v32, v6, v6
	v_pk_mul_f32 v[8:9], v[8:9], v[34:35] op_sel_hi:[1,0]
	v_fmac_f32_e32 v32, v7, v7
	v_fmac_f32_e32 v32, v8, v8
	v_pk_mul_f32 v[10:11], v[10:11], v[34:35] op_sel_hi:[1,0]
	v_fmac_f32_e32 v32, v9, v9
	v_fmac_f32_e32 v32, v10, v10
	v_pk_mul_f32 v[12:13], v[12:13], v[34:35] op_sel_hi:[1,0]
	v_fmac_f32_e32 v32, v11, v11
	v_fmac_f32_e32 v32, v12, v12
	v_pk_mul_f32 v[14:15], v[14:15], v[34:35] op_sel_hi:[1,0]
	v_fmac_f32_e32 v32, v13, v13
	v_fmac_f32_e32 v32, v14, v14
	v_fmac_f32_e32 v32, v15, v15
	v_mov_b32_e32 v33, v32
	s_nop 1
	v_permlane32_swap_b32_e32 v32, v33
	s_and_saveexec_b64 s[42:43], s[0:1]
	v_add_f32_e32 v32, v32, v33
	ds_write_b32 v72, v32 offset:128
	s_or_b64 exec, exec, s[42:43]
	v_lshlrev_b64 v[36:37], 1, v[184:185]
	v_lshl_add_u64 v[32:33], s[72:73], 0, v[188:189]
	v_lshlrev_b32_e32 v178, 1, v186
	v_lshl_add_u64 v[32:33], v[32:33], 0, v[36:37]
	v_lshl_add_u64 v[32:33], v[32:33], 0, v[178:179]
	v_add_co_u32_e32 v34, vcc, s46, v32
	s_waitcnt lgkmcnt(0)
	s_nop 0
	v_addc_co_u32_e32 v35, vcc, 0, v33, vcc
	s_barrier
	global_load_dwordx4 v[74:77], v[34:35], off offset:512
	v_lshl_add_u32 v72, v200, 2, 0
	ds_read2st64_b32 v[34:35], v72 offset1:1
	ds_read2st64_b32 v[50:51], v72 offset0:2 offset1:3
	ds_read2st64_b32 v[78:79], v72 offset0:4 offset1:5
	ds_read2st64_b32 v[80:81], v72 offset0:6 offset1:7
	v_mov_b32_e32 v82, v65
	s_waitcnt lgkmcnt(3)
	v_add_f32_e32 v34, 0, v34
	v_add_f32_e32 v34, v34, v35
	s_waitcnt lgkmcnt(2)
	v_add_f32_e32 v34, v34, v50
	v_add_f32_e32 v34, v34, v51
	s_waitcnt lgkmcnt(1)
	v_add_f32_e32 v34, v34, v78
	v_add_f32_e32 v34, v34, v79
	s_waitcnt lgkmcnt(0)
	v_add_f32_e32 v34, v34, v80
	v_add_f32_e32 v34, v34, v81
	v_fmamk_f32 v34, v34, 0x3b000000, v196
	v_mul_f32_e32 v35, 0x4b800000, v34
	v_cmp_gt_f32_e32 vcc, s35, v34
	v_mov_b32_e32 v78, v67
	v_mov_b32_e32 v80, v64
	v_cndmask_b32_e32 v34, v34, v35, vcc
	v_lshl_add_u64 v[36:37], s[20:21], 0, v[36:37]
	s_waitcnt vmcnt(2)
	v_lshl_add_u32 v164, v180, 3, s66
	s_mov_b32 s8, 0
	s_mov_b64 s[0:1], -1
	s_waitcnt vmcnt(0)
	v_mov_b32_e32 v73, v76
	s_nop 1
	v_permlane32_swap_b32_e32 v74, v73
	v_lshlrev_b32_e32 v51, 16, v74
	v_mul_f32_e32 v50, 0xbfb8aa3b, v51
	v_exp_f32_e32 v50, v50
	v_rsq_f32_e32 v76, v34
	v_mov_b32_e32 v83, v77
	s_nop 1
	v_permlane32_swap_b32_e32 v75, v83
	v_add_f32_e32 v34, 1.0, v50
	v_rcp_f32_e32 v35, v34
	v_mul_f32_e32 v50, 0x45800000, v76
	v_mov_b32_e32 v34, v70
	v_cndmask_b32_e32 v50, v76, v50, vcc
	v_pk_mul_f32 v[34:35], v[34:35], v[50:51]
	v_and_b32_e32 v51, 0xffff0000, v74
	v_mul_f32_e32 v70, 0xbfb8aa3b, v51
	v_exp_f32_e32 v74, v70
	v_mov_b32_e32 v70, v71
	v_mov_b32_e32 v76, v68
	v_mul_f32_e32 v34, v34, v35
	v_add_f32_e32 v71, 1.0, v74
	v_rcp_f32_e32 v71, v71
	s_nop 0
	v_pk_mul_f32 v[70:71], v[70:71], v[50:51]
	v_lshlrev_b32_e32 v51, 16, v75
	v_mul_f32_e32 v74, 0xbfb8aa3b, v51
	v_exp_f32_e32 v74, v74
	s_nop 0
	v_add_f32_e32 v74, 1.0, v74
	v_rcp_f32_e32 v77, v74
	v_mov_b32_e32 v74, v69
	v_pk_mul_f32 v[76:77], v[76:77], v[50:51]
	v_and_b32_e32 v51, 0xffff0000, v75
	v_mul_f32_e32 v68, 0xbfb8aa3b, v51
	v_exp_f32_e32 v68, v68
	v_mul_f32_e32 v67, v76, v77
	v_add_f32_e32 v68, 1.0, v68
	v_rcp_f32_e32 v75, v68
	s_nop 0
	v_pk_mul_f32 v[68:69], v[74:75], v[50:51]
	v_lshlrev_b32_e32 v51, 16, v73
	v_mul_f32_e32 v74, 0xbfb8aa3b, v51
	v_exp_f32_e32 v74, v74
	v_mul_f32_e32 v68, v68, v69
	v_add_f32_e32 v74, 1.0, v74
	v_rcp_f32_e32 v75, v74
	v_mov_b32_e32 v74, v66
	v_pk_mul_f32 v[74:75], v[74:75], v[50:51]
	v_and_b32_e32 v51, 0xffff0000, v73
	v_mul_f32_e32 v66, 0xbfb8aa3b, v51
	v_exp_f32_e32 v66, v66
	s_nop 0
	v_add_f32_e32 v66, 1.0, v66
	v_rcp_f32_e32 v79, v66
	s_nop 0
	v_pk_mul_f32 v[78:79], v[78:79], v[50:51]
	v_lshlrev_b32_e32 v51, 16, v83
	v_mul_f32_e32 v64, 0xbfb8aa3b, v51
	v_exp_f32_e32 v66, v64
	v_lshl_add_u64 v[64:65], v[32:33], 0, s[6:7]
	v_add_f32_e32 v35, 1.0, v66
	v_rcp_f32_e32 v81, v35
	v_mul_f32_e32 v35, v70, v71
	v_cvt_pk_bf16_f32 v66, v34, v35
	v_cvt_pk_bf16_f32 v67, v67, v68
	v_pk_mul_f32 v[34:35], v[80:81], v[50:51]
	v_and_b32_e32 v51, 0xffff0000, v83
	v_mul_f32_e32 v70, 0xbfb8aa3b, v51
	v_exp_f32_e32 v70, v70
	v_mul_f32_e32 v68, v74, v75
	v_mov_b32_e32 v80, v63
	v_add_f32_e32 v69, 1.0, v70
	v_rcp_f32_e32 v83, v69
	v_mul_f32_e32 v69, v78, v79
	v_cvt_pk_bf16_f32 v68, v68, v69
	v_mul_f32_e32 v69, v34, v35
	v_pk_mul_f32 v[34:35], v[82:83], v[50:51]
	v_permlane32_swap_b32_e32 v66, v68
	v_mul_f32_e32 v34, v34, v35
	v_cvt_pk_bf16_f32 v69, v69, v34
	global_load_dwordx4 v[74:77], v[64:65], off offset:32
	v_permlane32_swap_b32_e32 v67, v69
	s_waitcnt vmcnt(0)
	v_mov_b32_e32 v73, v76
	s_nop 1
	v_permlane32_swap_b32_e32 v74, v73
	v_lshlrev_b32_e32 v51, 16, v74
	v_mul_f32_e32 v34, 0xbfb8aa3b, v51
	v_exp_f32_e32 v34, v34
	v_mov_b32_e32 v81, v77
	s_nop 1
	v_permlane32_swap_b32_e32 v75, v81
	v_add_f32_e32 v34, 1.0, v34
	v_rcp_f32_e32 v35, v34
	v_mov_b32_e32 v34, v56
	v_pk_mul_f32 v[70:71], v[34:35], v[50:51]
	v_and_b32_e32 v51, 0xffff0000, v74
	v_mul_f32_e32 v34, 0xbfb8aa3b, v51
	v_exp_f32_e32 v35, v34
	v_mov_b32_e32 v34, v57
	v_add_f32_e32 v35, 1.0, v35
	v_rcp_f32_e32 v35, v35
	s_nop 0
	v_pk_mul_f32 v[76:77], v[34:35], v[50:51]
	v_lshlrev_b32_e32 v51, 16, v75
	v_mul_f32_e32 v34, 0xbfb8aa3b, v51
	v_exp_f32_e32 v34, v34
	s_nop 0
	v_add_f32_e32 v34, 1.0, v34
	v_rcp_f32_e32 v35, v34
	v_mov_b32_e32 v34, v58
	v_mov_b32_e32 v58, v61
	v_pk_mul_f32 v[78:79], v[34:35], v[50:51]
	v_and_b32_e32 v51, 0xffff0000, v75
	v_mul_f32_e32 v34, 0xbfb8aa3b, v51
	v_exp_f32_e32 v34, v34
	s_nop 0
	v_add_f32_e32 v34, 1.0, v34
	v_rcp_f32_e32 v35, v34
	v_mov_b32_e32 v34, v59
	v_pk_mul_f32 v[74:75], v[34:35], v[50:51]
	v_lshlrev_b32_e32 v51, 16, v73
	v_mul_f32_e32 v34, 0xbfb8aa3b, v51
	v_exp_f32_e32 v56, v34
	v_lshlrev_b64 v[34:35], 11, v[182:183]
	v_add_f32_e32 v56, 1.0, v56
	v_rcp_f32_e32 v57, v56
	v_mov_b32_e32 v56, v60
	v_pk_mul_f32 v[60:61], v[56:57], v[50:51]
	v_and_b32_e32 v51, 0xffff0000, v73
	v_mul_f32_e32 v56, 0xbfb8aa3b, v51
	v_exp_f32_e32 v59, v56
	v_lshl_add_u64 v[56:57], v[36:37], 0, v[34:35]
	v_lshl_add_u64 v[56:57], v[56:57], 0, v[178:179]
	global_store_dwordx4 v[56:57], v[66:69], off
	v_add_f32_e32 v59, 1.0, v59
	v_rcp_f32_e32 v59, v59
	v_mul_f32_e32 v60, v60, v61
	v_mul_f32_e32 v67, v74, v75
	v_mov_b32_e32 v74, v39
	v_pk_mul_f32 v[82:83], v[58:59], v[50:51]
	v_lshlrev_b32_e32 v51, 16, v81
	v_mul_f32_e32 v58, 0xbfb8aa3b, v51
	v_exp_f32_e32 v58, v58
	v_mul_f32_e32 v59, v70, v71
	v_or_b32_e32 v34, 0x10000, v34
	v_add_f32_e32 v58, 1.0, v58
	v_rcp_f32_e32 v63, v58
	v_mul_f32_e32 v58, v76, v77
	v_cvt_pk_bf16_f32 v58, v59, v58
	v_mul_f32_e32 v59, v78, v79
	v_pk_mul_f32 v[62:63], v[62:63], v[50:51]
	v_and_b32_e32 v51, 0xffff0000, v81
	v_mul_f32_e32 v66, 0xbfb8aa3b, v51
	v_exp_f32_e32 v66, v66
	v_cvt_pk_bf16_f32 v59, v59, v67
	s_nop 0
	v_add_f32_e32 v61, 1.0, v66
	v_rcp_f32_e32 v81, v61
	v_mul_f32_e32 v61, v82, v83
	v_cvt_pk_bf16_f32 v60, v60, v61
	v_mul_f32_e32 v61, v62, v63
	v_pk_mul_f32 v[62:63], v[80:81], v[50:51]
	v_permlane32_swap_b32_e32 v58, v60
	v_mul_f32_e32 v51, v62, v63
	v_cvt_pk_bf16_f32 v61, v61, v51
	global_load_dwordx4 v[66:69], v[64:65], off offset:64
	v_permlane32_swap_b32_e32 v59, v61
	global_store_dwordx4 v[56:57], v[58:61], off offset:32
	s_waitcnt vmcnt(1)
	v_mov_b32_e32 v73, v68
	s_nop 1
	v_permlane32_swap_b32_e32 v66, v73
	v_lshlrev_b32_e32 v51, 16, v66
	v_mul_f32_e32 v62, 0xbfb8aa3b, v51
	v_exp_f32_e32 v62, v62
	v_mov_b32_e32 v75, v69
	s_nop 1
	v_permlane32_swap_b32_e32 v67, v75
	v_add_f32_e32 v62, 1.0, v62
	v_rcp_f32_e32 v63, v62
	v_mov_b32_e32 v62, v54
	v_mov_b32_e32 v68, v52
	v_pk_mul_f32 v[62:63], v[62:63], v[50:51]
	v_and_b32_e32 v51, 0xffff0000, v66
	v_mul_f32_e32 v54, 0xbfb8aa3b, v51
	v_exp_f32_e32 v66, v54
	v_mov_b32_e32 v54, v55
	v_add_f32_e32 v55, 1.0, v66
	v_rcp_f32_e32 v55, v55
	s_nop 0
	v_pk_mul_f32 v[54:55], v[54:55], v[50:51]
	v_lshlrev_b32_e32 v51, 16, v67
	v_mul_f32_e32 v66, 0xbfb8aa3b, v51
	v_exp_f32_e32 v66, v66
	s_nop 0
	v_add_f32_e32 v66, 1.0, v66
	v_rcp_f32_e32 v69, v66
	v_mov_b32_e32 v66, v53
	v_pk_mul_f32 v[68:69], v[68:69], v[50:51]
	v_and_b32_e32 v51, 0xffff0000, v67
	v_mul_f32_e32 v52, 0xbfb8aa3b, v51
	v_exp_f32_e32 v52, v52
	s_nop 0
	v_add_f32_e32 v52, 1.0, v52
	v_rcp_f32_e32 v67, v52
	s_nop 0
	v_pk_mul_f32 v[66:67], v[66:67], v[50:51]
	v_lshlrev_b32_e32 v51, 16, v73
	v_mul_f32_e32 v52, 0xbfb8aa3b, v51
	v_exp_f32_e32 v52, v52
	s_nop 0
	v_add_f32_e32 v52, 1.0, v52
	v_rcp_f32_e32 v53, v52
	v_mov_b32_e32 v52, v48
	v_pk_mul_f32 v[70:71], v[52:53], v[50:51]
	v_and_b32_e32 v51, 0xffff0000, v73
	v_mul_f32_e32 v48, 0xbfb8aa3b, v51
	v_exp_f32_e32 v52, v48
	v_mov_b32_e32 v48, v49
	v_mul_f32_e32 v53, v54, v55
	v_mul_f32_e32 v55, v66, v67
	v_add_f32_e32 v49, 1.0, v52
	v_rcp_f32_e32 v49, v49
	v_mul_f32_e32 v52, v62, v63
	v_cvt_pk_bf16_f32 v52, v52, v53
	v_mul_f32_e32 v53, v68, v69
	v_pk_mul_f32 v[48:49], v[48:49], v[50:51]
	v_lshlrev_b32_e32 v51, 16, v75
	v_mul_f32_e32 v39, 0xbfb8aa3b, v51
	v_exp_f32_e32 v39, v39
	v_mul_f32_e32 v48, v48, v49
	v_cvt_pk_bf16_f32 v53, v53, v55
	v_mul_f32_e32 v55, v70, v71
	v_add_f32_e32 v39, 1.0, v39
	v_rcp_f32_e32 v39, v39
	s_nop 0
	v_pk_mul_f32 v[38:39], v[38:39], v[50:51]
	v_and_b32_e32 v51, 0xffff0000, v75
	v_mul_f32_e32 v54, 0xbfb8aa3b, v51
	v_exp_f32_e32 v54, v54
	s_nop 0
	v_add_f32_e32 v54, 1.0, v54
	v_rcp_f32_e32 v75, v54
	v_cvt_pk_bf16_f32 v54, v55, v48
	v_mul_f32_e32 v48, v38, v39
	v_permlane32_swap_b32_e32 v52, v54
	v_pk_mul_f32 v[38:39], v[74:75], v[50:51]
	s_nop 0
	v_mul_f32_e32 v38, v38, v39
	v_cvt_pk_bf16_f32 v55, v48, v38
	global_load_dwordx4 v[58:61], v[64:65], off offset:96
	v_permlane32_swap_b32_e32 v53, v55
	global_store_dwordx4 v[56:57], v[52:55], off offset:64
	s_waitcnt vmcnt(1)
	v_permlane32_swap_b32_e32 v58, v60
	v_lshlrev_b32_e32 v51, 16, v58
	v_mul_f32_e32 v38, 0xbfb8aa3b, v51
	v_exp_f32_e32 v38, v38
	v_permlane32_swap_b32_e32 v59, v61
	v_add_u32_e32 v52, 0x80, v72
	v_add_f32_e32 v38, 1.0, v38
	v_rcp_f32_e32 v39, v38
	v_mov_b32_e32 v38, v40
	v_pk_mul_f32 v[38:39], v[38:39], v[50:51]
	v_and_b32_e32 v51, 0xffff0000, v58
	v_mul_f32_e32 v40, 0xbfb8aa3b, v51
	v_exp_f32_e32 v48, v40
	v_mov_b32_e32 v40, v41
	v_mov_b32_e32 v58, v43
	v_mul_f32_e32 v38, v38, v39
	v_add_f32_e32 v41, 1.0, v48
	v_rcp_f32_e32 v41, v41
	s_nop 0
	v_pk_mul_f32 v[40:41], v[40:41], v[50:51]
	v_lshlrev_b32_e32 v51, 16, v59
	v_mul_f32_e32 v48, 0xbfb8aa3b, v51
	v_exp_f32_e32 v48, v48
	s_nop 0
	v_add_f32_e32 v48, 1.0, v48
	v_rcp_f32_e32 v49, v48
	v_mov_b32_e32 v48, v42
	v_pk_mul_f32 v[48:49], v[48:49], v[50:51]
	v_and_b32_e32 v51, 0xffff0000, v59
	v_mul_f32_e32 v42, 0xbfb8aa3b, v51
	v_exp_f32_e32 v42, v42
	s_nop 0
	v_add_f32_e32 v42, 1.0, v42
	v_rcp_f32_e32 v59, v42
	s_nop 0
	v_pk_mul_f32 v[42:43], v[58:59], v[50:51]
	v_lshlrev_b32_e32 v51, 16, v60
	v_mul_f32_e32 v58, 0xbfb8aa3b, v51
	v_exp_f32_e32 v58, v58
	v_mul_f32_e32 v42, v42, v43
	v_add_f32_e32 v58, 1.0, v58
	v_rcp_f32_e32 v59, v58
	v_mov_b32_e32 v58, v44
	v_pk_mul_f32 v[58:59], v[58:59], v[50:51]
	v_and_b32_e32 v51, 0xffff0000, v60
	v_mul_f32_e32 v44, 0xbfb8aa3b, v51
	v_exp_f32_e32 v62, v44
	v_mov_b32_e32 v44, v45
	v_mov_b32_e32 v60, v47
	v_add_f32_e32 v45, 1.0, v62
	v_rcp_f32_e32 v45, v45
	v_add_co_u32_e32 v62, vcc, s47, v32
	v_pk_mul_f32 v[44:45], v[44:45], v[50:51]
	v_lshlrev_b32_e32 v51, 16, v61
	v_mul_f32_e32 v47, 0xbfb8aa3b, v51
	v_exp_f32_e32 v47, v47
	v_addc_co_u32_e32 v63, vcc, 0, v33, vcc
	v_add_f32_e32 v39, 1.0, v47
	v_rcp_f32_e32 v47, v39
	v_mul_f32_e32 v39, v40, v41
	v_cvt_pk_bf16_f32 v40, v38, v39
	v_mul_f32_e32 v41, v48, v49
	v_pk_mul_f32 v[38:39], v[46:47], v[50:51]
	v_and_b32_e32 v51, 0xffff0000, v61
	v_mul_f32_e32 v46, 0xbfb8aa3b, v51
	v_exp_f32_e32 v46, v46
	v_cvt_pk_bf16_f32 v41, v41, v42
	v_mul_f32_e32 v42, v58, v59
	v_add_f32_e32 v43, 1.0, v46
	v_rcp_f32_e32 v61, v43
	v_mul_f32_e32 v43, v44, v45
	v_cvt_pk_bf16_f32 v42, v42, v43
	v_mul_f32_e32 v43, v38, v39
	v_pk_mul_f32 v[38:39], v[60:61], v[50:51]
	v_permlane32_swap_b32_e32 v40, v42
	v_mul_f32_e32 v38, v38, v39
	v_cvt_pk_bf16_f32 v43, v43, v38
	global_load_dwordx4 v[44:47], v[62:63], off offset:512
	ds_read2_b32 v[38:39], v72 offset0:32 offset1:96
	ds_read2_b32 v[48:49], v72 offset0:160 offset1:224
	ds_read2st64_b32 v[50:51], v52 offset0:4 offset1:5
	ds_read2st64_b32 v[52:53], v52 offset0:6 offset1:7
	v_permlane32_swap_b32_e32 v41, v43
	global_store_dwordx4 v[56:57], v[40:43], off offset:96
	s_waitcnt lgkmcnt(3)
	v_add_f32_e32 v38, 0, v38
	v_add_f32_e32 v38, v38, v39
	s_waitcnt lgkmcnt(2)
	v_add_f32_e32 v38, v38, v48
	v_add_f32_e32 v38, v38, v49
	s_waitcnt lgkmcnt(1)
	v_add_f32_e32 v38, v38, v50
	v_add_f32_e32 v38, v38, v51
	s_waitcnt lgkmcnt(0)
	v_add_f32_e32 v38, v38, v52
	v_add_f32_e32 v38, v38, v53
	v_fmamk_f32 v38, v38, 0x3b000000, v196
	v_mul_f32_e32 v48, 0x4b800000, v38
	v_cmp_gt_f32_e32 vcc, s35, v38
	s_waitcnt vmcnt(1)
	v_mov_b32_e32 v52, v46
	s_nop 1
	v_permlane32_swap_b32_e32 v44, v52
	v_lshlrev_b32_e32 v39, 16, v44
	v_mul_f32_e32 v46, 0xbfb8aa3b, v39
	v_exp_f32_e32 v46, v46
	v_cndmask_b32_e32 v38, v38, v48, vcc
	v_rsq_f32_e32 v38, v38
	v_mov_b32_e32 v48, v16
	v_add_f32_e32 v46, 1.0, v46
	v_rcp_f32_e32 v49, v46
	v_mul_f32_e32 v16, 0x45800000, v38
	v_cndmask_b32_e32 v38, v38, v16, vcc
	v_mov_b32_e32 v53, v47
	v_pk_mul_f32 v[48:49], v[48:49], v[38:39]
	v_and_b32_e32 v39, 0xffff0000, v44
	v_mul_f32_e32 v16, 0xbfb8aa3b, v39
	v_exp_f32_e32 v44, v16
	v_mov_b32_e32 v16, v17
	v_permlane32_swap_b32_e32 v45, v53
	v_add_f32_e32 v17, 1.0, v44
	v_rcp_f32_e32 v17, v17
	v_mov_b32_e32 v46, v18
	v_pk_mul_f32 v[16:17], v[16:17], v[38:39]
	v_lshlrev_b32_e32 v39, 16, v45
	v_mul_f32_e32 v44, 0xbfb8aa3b, v39
	v_exp_f32_e32 v44, v44
	v_mul_f32_e32 v16, v16, v17
	v_add_f32_e32 v44, 1.0, v44
	v_rcp_f32_e32 v47, v44
	v_mov_b32_e32 v44, v19
	v_pk_mul_f32 v[46:47], v[46:47], v[38:39]
	v_and_b32_e32 v39, 0xffff0000, v45
	v_mul_f32_e32 v18, 0xbfb8aa3b, v39
	v_exp_f32_e32 v18, v18
	s_nop 0
	v_add_f32_e32 v18, 1.0, v18
	v_rcp_f32_e32 v45, v18
	s_nop 0
	v_pk_mul_f32 v[44:45], v[44:45], v[38:39]
	v_lshlrev_b32_e32 v39, 16, v52
	v_mul_f32_e32 v18, 0xbfb8aa3b, v39
	v_exp_f32_e32 v18, v18
	s_nop 0
	v_add_f32_e32 v18, 1.0, v18
	v_rcp_f32_e32 v19, v18
	v_mov_b32_e32 v18, v20
	v_mov_b32_e32 v20, v21
	v_pk_mul_f32 v[50:51], v[18:19], v[38:39]
	v_and_b32_e32 v39, 0xffff0000, v52
	v_mul_f32_e32 v18, 0xbfb8aa3b, v39
	v_exp_f32_e32 v18, v18
	v_mov_b32_e32 v52, v23
	v_add_f32_e32 v18, 1.0, v18
	v_rcp_f32_e32 v21, v18
	v_lshl_add_u64 v[18:19], v[32:33], 0, s[12:13]
	v_pk_mul_f32 v[32:33], v[20:21], v[38:39]
	v_lshlrev_b32_e32 v39, 16, v53
	v_mul_f32_e32 v20, 0xbfb8aa3b, v39
	v_exp_f32_e32 v20, v20
	v_mul_f32_e32 v21, v48, v49
	v_add_f32_e32 v20, 1.0, v20
	v_rcp_f32_e32 v23, v20
	v_cvt_pk_bf16_f32 v20, v21, v16
	v_mul_f32_e32 v21, v46, v47
	v_pk_mul_f32 v[16:17], v[22:23], v[38:39]
	v_and_b32_e32 v39, 0xffff0000, v53
	v_mul_f32_e32 v22, 0xbfb8aa3b, v39
	v_exp_f32_e32 v22, v22
	v_mul_f32_e32 v23, v44, v45
	v_cvt_pk_bf16_f32 v21, v21, v23
	v_mul_f32_e32 v23, v50, v51
	v_add_f32_e32 v22, 1.0, v22
	v_rcp_f32_e32 v53, v22
	v_mul_f32_e32 v22, v32, v33
	v_cvt_pk_bf16_f32 v22, v23, v22
	v_mul_f32_e32 v23, v16, v17
	v_pk_mul_f32 v[16:17], v[52:53], v[38:39]
	v_permlane32_swap_b32_e32 v20, v22
	v_mul_f32_e32 v16, v16, v17
	v_cvt_pk_bf16_f32 v23, v23, v16
	global_load_dwordx4 v[40:43], v[18:19], off offset:32
	v_permlane32_swap_b32_e32 v21, v23
	s_waitcnt vmcnt(0)
	v_mov_b32_e32 v44, v42
	s_nop 1
	v_permlane32_swap_b32_e32 v40, v44
	v_lshlrev_b32_e32 v39, 16, v40
	v_mul_f32_e32 v16, 0xbfb8aa3b, v39
	v_exp_f32_e32 v16, v16
	v_mov_b32_e32 v45, v43
	s_nop 1
	v_permlane32_swap_b32_e32 v41, v45
	v_add_f32_e32 v16, 1.0, v16
	v_rcp_f32_e32 v17, v16
	v_mov_b32_e32 v16, v24
	v_pk_mul_f32 v[32:33], v[16:17], v[38:39]
	v_and_b32_e32 v39, 0xffff0000, v40
	v_mul_f32_e32 v16, 0xbfb8aa3b, v39
	v_exp_f32_e32 v17, v16
	v_mov_b32_e32 v16, v25
	v_add_f32_e32 v17, 1.0, v17
	v_rcp_f32_e32 v17, v17
	s_nop 0
	v_pk_mul_f32 v[24:25], v[16:17], v[38:39]
	v_lshlrev_b32_e32 v39, 16, v41
	v_mul_f32_e32 v16, 0xbfb8aa3b, v39
	v_exp_f32_e32 v16, v16
	s_nop 0
	v_add_f32_e32 v16, 1.0, v16
	v_rcp_f32_e32 v17, v16
	v_mov_b32_e32 v16, v26
	v_pk_mul_f32 v[42:43], v[16:17], v[38:39]
	v_and_b32_e32 v39, 0xffff0000, v41
	v_mul_f32_e32 v16, 0xbfb8aa3b, v39
	v_exp_f32_e32 v16, v16
	s_nop 0
	v_add_f32_e32 v16, 1.0, v16
	v_rcp_f32_e32 v17, v16
	v_mov_b32_e32 v16, v27
	v_pk_mul_f32 v[26:27], v[16:17], v[38:39]
	v_lshlrev_b32_e32 v39, 16, v44
	v_mul_f32_e32 v16, 0xbfb8aa3b, v39
	v_exp_f32_e32 v16, v16
	s_nop 0
	v_add_f32_e32 v16, 1.0, v16
	v_rcp_f32_e32 v17, v16
	v_mov_b32_e32 v16, v28
	v_mov_b32_e32 v28, v29
	v_pk_mul_f32 v[40:41], v[16:17], v[38:39]
	v_and_b32_e32 v39, 0xffff0000, v44
	v_mul_f32_e32 v16, 0xbfb8aa3b, v39
	v_exp_f32_e32 v29, v16
	v_mov_b32_e32 v44, v31
	v_lshl_add_u64 v[16:17], v[36:37], 0, v[34:35]
	v_lshl_add_u64 v[16:17], v[16:17], 0, v[178:179]
	v_add_f32_e32 v29, 1.0, v29
	v_rcp_f32_e32 v29, v29
	global_store_dwordx4 v[16:17], v[20:23], off
	v_lshlrev_b32_e32 v178, 5, v199
	v_pk_mul_f32 v[28:29], v[28:29], v[38:39]
	v_lshlrev_b32_e32 v39, 16, v45
	v_mul_f32_e32 v31, 0xbfb8aa3b, v39
	v_exp_f32_e32 v31, v31
	v_mul_f32_e32 v20, v32, v33
	v_mul_f32_e32 v23, v26, v27
	v_add_f32_e32 v21, 1.0, v31
	v_rcp_f32_e32 v31, v21
	v_mul_f32_e32 v21, v24, v25
	v_cvt_pk_bf16_f32 v20, v20, v21
	v_mul_f32_e32 v21, v42, v43
	v_pk_mul_f32 v[24:25], v[30:31], v[38:39]
	v_and_b32_e32 v39, 0xffff0000, v45
	v_mul_f32_e32 v22, 0xbfb8aa3b, v39
	v_exp_f32_e32 v22, v22
	v_cvt_pk_bf16_f32 v21, v21, v23
	v_mul_f32_e32 v23, v40, v41
	v_add_f32_e32 v22, 1.0, v22
	v_rcp_f32_e32 v45, v22
	v_mul_f32_e32 v22, v28, v29
	v_cvt_pk_bf16_f32 v22, v23, v22
	v_mul_f32_e32 v23, v24, v25
	v_pk_mul_f32 v[24:25], v[44:45], v[38:39]
	v_mov_b32_e32 v28, v0
	v_mul_f32_e32 v24, v24, v25
	v_cvt_pk_bf16_f32 v23, v23, v24
	global_load_dwordx4 v[24:27], v[18:19], off offset:64
	v_permlane32_swap_b32_e32 v20, v22
	v_permlane32_swap_b32_e32 v21, v23
	global_store_dwordx4 v[16:17], v[20:23], off offset:32
	s_waitcnt vmcnt(1)
	v_mov_b32_e32 v30, v26
	s_nop 1
	v_permlane32_swap_b32_e32 v24, v30
	v_lshlrev_b32_e32 v39, 16, v24
	v_mul_f32_e32 v26, 0xbfb8aa3b, v39
	v_exp_f32_e32 v26, v26
	v_mov_b32_e32 v31, v27
	s_nop 1
	v_permlane32_swap_b32_e32 v25, v31
	v_add_f32_e32 v26, 1.0, v26
	v_rcp_f32_e32 v29, v26
	v_mov_b32_e32 v26, v2
	v_lshl_add_u64 v[22:23], s[60:61], 0, v[178:179]
	v_pk_mul_f32 v[28:29], v[28:29], v[38:39]
	v_and_b32_e32 v39, 0xffff0000, v24
	v_mul_f32_e32 v0, 0xbfb8aa3b, v39
	v_exp_f32_e32 v24, v0
	v_mov_b32_e32 v0, v1
	v_mul_f32_e32 v20, v28, v29
	v_add_f32_e32 v1, 1.0, v24
	v_rcp_f32_e32 v1, v1
	s_nop 0
	v_pk_mul_f32 v[0:1], v[0:1], v[38:39]
	v_lshlrev_b32_e32 v39, 16, v25
	v_mul_f32_e32 v24, 0xbfb8aa3b, v39
	v_exp_f32_e32 v24, v24
	v_mul_f32_e32 v0, v0, v1
	v_cvt_pk_bf16_f32 v0, v20, v0
	v_add_f32_e32 v24, 1.0, v24
	v_rcp_f32_e32 v27, v24
	v_mov_b32_e32 v24, v3
	v_pk_mul_f32 v[26:27], v[26:27], v[38:39]
	v_and_b32_e32 v39, 0xffff0000, v25
	v_mul_f32_e32 v2, 0xbfb8aa3b, v39
	v_exp_f32_e32 v2, v2
	v_mul_f32_e32 v1, v26, v27
	v_add_f32_e32 v2, 1.0, v2
	v_rcp_f32_e32 v25, v2
	s_nop 0
	v_pk_mul_f32 v[2:3], v[24:25], v[38:39]
	v_lshlrev_b32_e32 v39, 16, v30
	v_mul_f32_e32 v24, 0xbfb8aa3b, v39
	v_exp_f32_e32 v24, v24
	v_mul_f32_e32 v2, v2, v3
	v_cvt_pk_bf16_f32 v1, v1, v2
	v_add_f32_e32 v24, 1.0, v24
	v_rcp_f32_e32 v25, v24
	v_mov_b32_e32 v24, v4
	v_pk_mul_f32 v[24:25], v[24:25], v[38:39]
	v_and_b32_e32 v39, 0xffff0000, v30
	v_mul_f32_e32 v4, 0xbfb8aa3b, v39
	v_exp_f32_e32 v30, v4
	v_mov_b32_e32 v4, v5
	v_mul_f32_e32 v2, v24, v25
	v_lshl_add_u64 v[24:25], v[22:23], 0, s[36:37]
	v_add_f32_e32 v5, 1.0, v30
	v_rcp_f32_e32 v5, v5
	v_mov_b32_e32 v30, v7
	v_pk_mul_f32 v[4:5], v[4:5], v[38:39]
	v_lshlrev_b32_e32 v39, 16, v31
	v_mul_f32_e32 v7, 0xbfb8aa3b, v39
	v_exp_f32_e32 v7, v7
	s_nop 0
	v_add_f32_e32 v7, 1.0, v7
	v_rcp_f32_e32 v7, v7
	s_nop 0
	v_pk_mul_f32 v[6:7], v[6:7], v[38:39]
	v_and_b32_e32 v39, 0xffff0000, v31
	v_mul_f32_e32 v20, 0xbfb8aa3b, v39
	v_exp_f32_e32 v20, v20
	s_nop 0
	v_add_f32_e32 v3, 1.0, v20
	v_rcp_f32_e32 v31, v3
	v_mul_f32_e32 v3, v4, v5
	v_cvt_pk_bf16_f32 v2, v2, v3
	v_mul_f32_e32 v3, v6, v7
	v_pk_mul_f32 v[4:5], v[30:31], v[38:39]
	v_permlane32_swap_b32_e32 v0, v2
	v_mul_f32_e32 v4, v4, v5
	v_cvt_pk_bf16_f32 v3, v3, v4
	global_load_dwordx4 v[4:7], v[18:19], off offset:96
	v_mov_b32_e32 v18, v8
	v_mov_b32_e32 v8, v9
	v_permlane32_swap_b32_e32 v1, v3
	global_store_dwordx4 v[16:17], v[0:3], off offset:64
	v_mov_b32_e32 v20, v15
	s_waitcnt vmcnt(1)
	v_mov_b32_e32 v21, v6
	s_nop 1
	v_permlane32_swap_b32_e32 v4, v21
	v_lshlrev_b32_e32 v39, 16, v4
	v_mul_f32_e32 v6, 0xbfb8aa3b, v39
	v_exp_f32_e32 v6, v6
	v_mov_b32_e32 v26, v7
	s_nop 1
	v_permlane32_swap_b32_e32 v5, v26
	v_add_f32_e32 v6, 1.0, v6
	v_rcp_f32_e32 v19, v6
	s_nop 0
	v_pk_mul_f32 v[18:19], v[18:19], v[38:39]
	v_and_b32_e32 v39, 0xffff0000, v4
	v_mul_f32_e32 v4, 0xbfb8aa3b, v39
	v_exp_f32_e32 v4, v4
	s_nop 0
	v_add_f32_e32 v4, 1.0, v4
	v_rcp_f32_e32 v9, v4
	s_nop 0
	v_pk_mul_f32 v[6:7], v[8:9], v[38:39]
	v_lshlrev_b32_e32 v39, 16, v5
	v_mul_f32_e32 v4, 0xbfb8aa3b, v39
	v_exp_f32_e32 v4, v4
	v_mov_b32_e32 v8, v10
	v_mul_f32_e32 v6, v6, v7
	v_add_f32_e32 v4, 1.0, v4
	v_rcp_f32_e32 v9, v4
	s_nop 0
	v_pk_mul_f32 v[8:9], v[8:9], v[38:39]
	v_and_b32_e32 v39, 0xffff0000, v5
	v_mul_f32_e32 v4, 0xbfb8aa3b, v39
	v_exp_f32_e32 v4, v4
	s_nop 0
	v_add_f32_e32 v4, 1.0, v4
	v_rcp_f32_e32 v5, v4
	v_mov_b32_e32 v4, v11
	v_pk_mul_f32 v[4:5], v[4:5], v[38:39]
	v_lshlrev_b32_e32 v39, 16, v21
	v_mul_f32_e32 v10, 0xbfb8aa3b, v39
	v_exp_f32_e32 v11, v10
	v_mov_b32_e32 v10, v13
	v_mul_f32_e32 v4, v4, v5
	v_add_f32_e32 v11, 1.0, v11
	v_rcp_f32_e32 v13, v11
	s_nop 0
	v_pk_mul_f32 v[12:13], v[12:13], v[38:39]
	v_and_b32_e32 v39, 0xffff0000, v21
	v_mul_f32_e32 v11, 0xbfb8aa3b, v39
	v_exp_f32_e32 v11, v11
	v_mul_f32_e32 v7, v12, v13
	v_add_co_u32_e32 v12, vcc, s46, v22
	v_add_f32_e32 v11, 1.0, v11
	v_rcp_f32_e32 v11, v11
	v_addc_co_u32_e32 v13, vcc, 0, v23, vcc
	v_cmp_gt_u32_e32 vcc, s46, v164
	v_pk_mul_f32 v[2:3], v[10:11], v[38:39]
	v_lshlrev_b32_e32 v39, 16, v26
	v_mul_f32_e32 v0, 0xbfb8aa3b, v39
	v_exp_f32_e32 v1, v0
	v_mul_f32_e32 v0, v18, v19
	v_cvt_pk_bf16_f32 v0, v0, v6
	v_mul_f32_e32 v2, v2, v3
	v_add_f32_e32 v1, 1.0, v1
	v_rcp_f32_e32 v15, v1
	v_mul_f32_e32 v1, v8, v9
	v_cvt_pk_bf16_f32 v1, v1, v4
	v_cvt_pk_bf16_f32 v2, v7, v2
	v_pk_mul_f32 v[4:5], v[14:15], v[38:39]
	v_and_b32_e32 v39, 0xffff0000, v26
	v_mul_f32_e32 v6, 0xbfb8aa3b, v39
	v_exp_f32_e32 v6, v6
	v_permlane32_swap_b32_e32 v0, v2
	v_cndmask_b32_e64 v65, 0, 1.0, vcc
	v_add_f32_e32 v3, 1.0, v6
	v_rcp_f32_e32 v21, v3
	v_mul_f32_e32 v3, v4, v5
	v_mov_b32_e32 v66, v65
	v_mov_b32_e32 v68, v65
	v_pk_mul_f32 v[4:5], v[20:21], v[38:39]
	v_mov_b32_e32 v69, v65
	v_mul_f32_e32 v4, v4, v5
	v_cvt_pk_bf16_f32 v3, v3, v4
	s_nop 0
	v_permlane32_swap_b32_e32 v1, v3
	global_store_dwordx4 v[16:17], v[0:3], off offset:96
	global_load_dwordx4 v[0:3], v178, s[60:61] offset:16
	s_nop 0
	global_load_dwordx4 v[4:7], v[24:25], off offset:16
	global_load_dwordx4 v[8:11], v178, s[60:61]
	s_nop 0
	global_load_dwordx4 v[12:15], v[12:13], off
	s_nop 0
	global_load_dwordx4 v[16:19], v178, s[60:61] offset:2064
	global_load_dwordx4 v[20:23], v178, s[60:61] offset:2048
	v_lshlrev_b32_e32 v24, 3, v199
	v_lshlrev_b32_e32 v178, 4, v199
	v_lshl_add_u64 v[70:71], s[72:73], 0, v[178:179]
	v_lshl_add_u64 v[72:73], s[20:21], 0, v[178:179]
	v_lshlrev_b32_e32 v178, 1, v24
	s_waitcnt vmcnt(5)
	v_mov_b32_e32 v74, v2
	s_waitcnt vmcnt(4)
	v_mov_b32_e32 v75, v6
	v_mov_b32_e32 v76, v3
	v_mov_b32_e32 v77, v7
	v_mov_b32_e32 v78, v0
	v_mov_b32_e32 v79, v4
	v_mov_b32_e32 v80, v1
	v_mov_b32_e32 v81, v5
	s_waitcnt vmcnt(3)
	v_mov_b32_e32 v82, v10
	s_waitcnt vmcnt(2)
	v_mov_b32_e32 v83, v14
	v_mov_b32_e32 v84, v11
	v_mov_b32_e32 v85, v15
	v_mov_b32_e32 v86, v8
	v_mov_b32_e32 v87, v12
	v_mov_b32_e32 v88, v9
	v_mov_b32_e32 v89, v13
	v_mov_b32_e32 v90, v2
	s_waitcnt vmcnt(1)
	v_mov_b32_e32 v91, v18
	v_mov_b32_e32 v92, v3
	v_mov_b32_e32 v93, v19
	v_mov_b32_e32 v94, v0
	v_mov_b32_e32 v95, v16
	v_mov_b32_e32 v96, v1
	v_mov_b32_e32 v97, v17
	v_mov_b32_e32 v98, v10
	s_waitcnt vmcnt(0)
	v_mov_b32_e32 v99, v22
	v_mov_b32_e32 v100, v11
	v_mov_b32_e32 v101, v23
	v_mov_b32_e32 v102, v8
	v_mov_b32_e32 v103, v20
	v_mov_b32_e32 v104, v9
	v_mov_b32_e32 v105, v21
	v_mov_b32_e32 v106, v18
	v_mov_b32_e32 v107, v6
	v_mov_b32_e32 v108, v19
	v_mov_b32_e32 v109, v7
	v_mov_b32_e32 v110, v16
	v_mov_b32_e32 v111, v4
	v_mov_b32_e32 v112, v17
	v_mov_b32_e32 v113, v5
	v_mov_b32_e32 v114, v22
	v_mov_b32_e32 v115, v14
	v_mov_b32_e32 v116, v23
	v_mov_b32_e32 v117, v15
	v_mov_b32_e32 v118, v20
	v_mov_b32_e32 v119, v12
	v_mov_b32_e32 v120, v21
	v_mov_b32_e32 v121, v13
